# v087 + UP-phase filler weight-conversion stores write-through (sc1)
# speedup vs baseline: 1.0052x; 1.0052x over previous
.LBB0_1413:
	v_add_u32_e32 v11, 0x840, v19
	ds_write2_b32 v11, v6, v7 offset1:1
	v_add_u32_e32 v6, 0x848, v19
	ds_write2_b32 v6, v8, v9 offset1:1
	s_waitcnt vmcnt(0)
	v_pk_mul_f32 v[2:3], v[2:3], v[10:11] op_sel_hi:[1,0]
	v_add_u32_e32 v6, 0xc60, v19
	ds_write2_b32 v6, v2, v3 offset1:1
	v_pk_mul_f32 v[2:3], v[4:5], v[10:11] op_sel_hi:[1,0]
	v_add_u32_e32 v4, 0xc68, v19
	ds_write2_b32 v4, v2, v3 offset1:1
	s_waitcnt lgkmcnt(0)
	ds_read2_b32 v[8:9], v50 offset0:33 offset1:41
	ds_read2_b32 v[10:11], v50 offset1:8
	s_lshl_b64 s[0:1], s[36:37], 21
	v_readlane_b32 s14, v252, 59
	s_add_u32 s0, s14, s0
	v_readlane_b32 s14, v252, 60
	ds_read2_b32 v[12:13], v50 offset0:66 offset1:74
	ds_read2_b32 v[14:15], v50 offset0:99 offset1:107
	ds_read2_b32 v[16:17], v50 offset0:132 offset1:140
	ds_read2_b32 v[18:19], v50 offset0:165 offset1:173
	ds_read2_b32 v[20:21], v50 offset0:198 offset1:206
	ds_read2_b32 v[22:23], v50 offset0:231 offset1:239
	s_addc_u32 s1, s14, s1
	s_lshl_b32 s13, s13, 1
	s_add_u32 s0, s0, s13
	s_addc_u32 s1, s1, 0
	v_lshlrev_b32_e32 v98, 1, v36
	s_waitcnt lgkmcnt(6)
	v_cvt_pk_bf16_f32 v2, v10, v8
	v_or_b32_e32 v8, s12, v35
	v_lshl_add_u64 v[6:7], s[0:1], 0, v[98:99]
	v_lshlrev_b32_e32 v98, 11, v8
	v_or_b32_e32 v8, s12, v47
	s_waitcnt lgkmcnt(4)
	v_cvt_pk_bf16_f32 v3, v12, v14
	s_waitcnt lgkmcnt(2)
	v_cvt_pk_bf16_f32 v4, v16, v18
	s_waitcnt lgkmcnt(0)
	v_cvt_pk_bf16_f32 v5, v20, v22
	v_lshl_add_u64 v[24:25], v[6:7], 0, v[98:99]
	v_lshlrev_b32_e32 v98, 11, v8
	global_store_dwordx4 v[24:25], v[2:5], off sc1
	s_nop 1
	v_cvt_pk_bf16_f32 v2, v11, v9
	v_cvt_pk_bf16_f32 v3, v13, v15
	v_cvt_pk_bf16_f32 v4, v17, v19
	v_cvt_pk_bf16_f32 v5, v21, v23
	v_lshl_add_u64 v[8:9], v[6:7], 0, v[98:99]
	global_store_dwordx4 v[8:9], v[2:5], off sc1
	ds_read2_b32 v[8:9], v50 offset0:49 offset1:57
	ds_read2_b32 v[10:11], v50 offset0:16 offset1:24
	ds_read2_b32 v[12:13], v50 offset0:82 offset1:90
	ds_read2_b32 v[14:15], v50 offset0:115 offset1:123
	ds_read2_b32 v[16:17], v50 offset0:148 offset1:156
	ds_read2_b32 v[18:19], v50 offset0:181 offset1:189
	ds_read2_b32 v[20:21], v50 offset0:214 offset1:222
	ds_read2_b32 v[22:23], v50 offset0:247 offset1:255
	s_waitcnt lgkmcnt(6)
	v_cvt_pk_bf16_f32 v2, v10, v8
	v_or_b32_e32 v8, s12, v48
	v_lshlrev_b32_e32 v98, 11, v8
	v_or_b32_e32 v8, s12, v49
	s_waitcnt lgkmcnt(4)
	v_cvt_pk_bf16_f32 v3, v12, v14
	s_waitcnt lgkmcnt(2)
	v_cvt_pk_bf16_f32 v4, v16, v18
	s_waitcnt lgkmcnt(0)
	v_cvt_pk_bf16_f32 v5, v20, v22
	v_lshl_add_u64 v[24:25], v[6:7], 0, v[98:99]
	v_lshlrev_b32_e32 v98, 11, v8
	global_store_dwordx4 v[24:25], v[2:5], off sc1
	v_lshl_add_u64 v[6:7], v[6:7], 0, v[98:99]
	s_nop 0
	v_cvt_pk_bf16_f32 v2, v11, v9
	v_cvt_pk_bf16_f32 v3, v13, v15
	v_cvt_pk_bf16_f32 v4, v17, v19
	v_cvt_pk_bf16_f32 v5, v21, v23
	global_store_dwordx4 v[6:7], v[2:5], off sc1
	s_waitcnt lgkmcnt(0)

.LBB0_1426:
	v_add_u32_e32 v11, 0x840, v19
	ds_write2_b32 v11, v6, v7 offset1:1
	v_add_u32_e32 v6, 0x848, v19
	ds_write2_b32 v6, v8, v9 offset1:1
	s_waitcnt vmcnt(0)
	v_pk_mul_f32 v[2:3], v[2:3], v[10:11] op_sel_hi:[1,0]
	v_add_u32_e32 v6, 0xc60, v19
	ds_write2_b32 v6, v2, v3 offset1:1
	v_pk_mul_f32 v[2:3], v[4:5], v[10:11] op_sel_hi:[1,0]
	v_add_u32_e32 v4, 0xc68, v19
	ds_write2_b32 v4, v2, v3 offset1:1
	s_waitcnt lgkmcnt(0)
	s_mul_i32 s1, s36, 0x150000
	s_mul_hi_i32 s0, s36, 0x150000
	s_add_u32 s1, s86, s1
	ds_read2_b32 v[8:9], v50 offset0:33 offset1:41
	ds_read2_b32 v[10:11], v50 offset1:8
	s_addc_u32 s14, s87, s0
	s_lshl_b32 s0, s13, 1
	s_add_u32 s0, s1, s0
	ds_read2_b32 v[12:13], v50 offset0:66 offset1:74
	ds_read2_b32 v[14:15], v50 offset0:99 offset1:107
	ds_read2_b32 v[16:17], v50 offset0:132 offset1:140
	ds_read2_b32 v[18:19], v50 offset0:165 offset1:173
	ds_read2_b32 v[20:21], v50 offset0:198 offset1:206
	ds_read2_b32 v[22:23], v50 offset0:231 offset1:239
	s_addc_u32 s1, s14, 0
	v_lshlrev_b32_e32 v98, 1, v36
	v_lshl_add_u64 v[2:3], s[0:1], 0, v[98:99]
	s_mov_b64 s[0:1], 0xc90000
	v_lshl_add_u64 v[6:7], v[2:3], 0, s[0:1]
	s_waitcnt lgkmcnt(6)
	v_cvt_pk_bf16_f32 v2, v10, v8
	v_or_b32_e32 v8, s12, v35
	v_mul_u32_u24_e32 v98, 0x300, v8
	v_or_b32_e32 v8, s12, v47
	s_waitcnt lgkmcnt(4)
	v_cvt_pk_bf16_f32 v3, v12, v14
	s_waitcnt lgkmcnt(2)
	v_cvt_pk_bf16_f32 v4, v16, v18
	s_waitcnt lgkmcnt(0)
	v_cvt_pk_bf16_f32 v5, v20, v22
	v_lshl_add_u64 v[24:25], v[6:7], 0, v[98:99]
	v_mul_u32_u24_e32 v98, 0x300, v8
	global_store_dwordx4 v[24:25], v[2:5], off sc1
	s_nop 1
	v_cvt_pk_bf16_f32 v2, v11, v9
	v_cvt_pk_bf16_f32 v3, v13, v15
	v_cvt_pk_bf16_f32 v4, v17, v19
	v_cvt_pk_bf16_f32 v5, v21, v23
	v_lshl_add_u64 v[8:9], v[6:7], 0, v[98:99]
	global_store_dwordx4 v[8:9], v[2:5], off sc1
	ds_read2_b32 v[8:9], v50 offset0:16 offset1:24
	ds_read2_b32 v[10:11], v50 offset0:49 offset1:57
	ds_read2_b32 v[12:13], v50 offset0:82 offset1:90
	ds_read2_b32 v[14:15], v50 offset0:115 offset1:123
	ds_read2_b32 v[16:17], v50 offset0:148 offset1:156
	ds_read2_b32 v[18:19], v50 offset0:181 offset1:189
	ds_read2_b32 v[20:21], v50 offset0:214 offset1:222
	ds_read2_b32 v[22:23], v50 offset0:247 offset1:255
	s_waitcnt lgkmcnt(6)
	v_cvt_pk_bf16_f32 v2, v8, v10
	v_or_b32_e32 v8, s12, v48
	v_mul_u32_u24_e32 v98, 0x300, v8
	v_or_b32_e32 v8, s12, v49
	s_waitcnt lgkmcnt(4)
	v_cvt_pk_bf16_f32 v3, v12, v14
	s_waitcnt lgkmcnt(2)
	v_cvt_pk_bf16_f32 v4, v16, v18
	s_waitcnt lgkmcnt(0)
	v_cvt_pk_bf16_f32 v5, v20, v22
	v_lshl_add_u64 v[24:25], v[6:7], 0, v[98:99]
	v_mul_u32_u24_e32 v98, 0x300, v8
	global_store_dwordx4 v[24:25], v[2:5], off sc1
	v_lshl_add_u64 v[6:7], v[6:7], 0, v[98:99]
	s_nop 0
	v_cvt_pk_bf16_f32 v2, v9, v11
	v_cvt_pk_bf16_f32 v3, v13, v15
	v_cvt_pk_bf16_f32 v4, v17, v19
	v_cvt_pk_bf16_f32 v5, v21, v23
	global_store_dwordx4 v[6:7], v[2:5], off sc1
	s_waitcnt lgkmcnt(0)

.LBB0_1439:
	v_add_u32_e32 v11, 0x840, v19
	ds_write2_b32 v11, v6, v7 offset1:1
	v_add_u32_e32 v6, 0x848, v19
	ds_write2_b32 v6, v8, v9 offset1:1
	s_waitcnt vmcnt(0)
	v_pk_mul_f32 v[2:3], v[2:3], v[10:11] op_sel_hi:[1,0]
	v_add_u32_e32 v6, 0xc60, v19
	ds_write2_b32 v6, v2, v3 offset1:1
	v_pk_mul_f32 v[2:3], v[4:5], v[10:11] op_sel_hi:[1,0]
	v_add_u32_e32 v4, 0xc68, v19
	s_lshl_b32 s15, s14, 5
	s_mul_i32 s1, s36, 0x150000
	v_readlane_b32 s16, v251, 46
	ds_write2_b32 v4, v2, v3 offset1:1
	s_mul_hi_i32 s0, s36, 0x150000
	s_add_u32 s1, s16, s1
	v_readlane_b32 s16, v251, 47
	s_mulk_i32 s14, 0xab
	s_waitcnt lgkmcnt(0)
	s_addc_u32 s16, s16, s0
	s_bfe_u32 s0, s14, 0x6000a
	s_mul_i32 s0, s0, 6
	ds_read2_b32 v[8:9], v50 offset0:33 offset1:41
	ds_read2_b32 v[10:11], v50 offset1:8
	s_sub_i32 s0, s13, s0
	s_and_b32 s0, s0, 0xff
	s_cmp_gt_u32 s0, 3
	s_cselect_b64 vcc, -1, 0
	s_lshl_b32 s0, s12, 1
	ds_read2_b32 v[12:13], v50 offset0:66 offset1:74
	ds_read2_b32 v[14:15], v50 offset0:99 offset1:107
	ds_read2_b32 v[16:17], v50 offset0:132 offset1:140
	ds_read2_b32 v[18:19], v50 offset0:165 offset1:173
	ds_read2_b32 v[20:21], v50 offset0:198 offset1:206
	ds_read2_b32 v[22:23], v50 offset0:231 offset1:239
	s_add_u32 s0, s1, s0
	s_waitcnt lgkmcnt(6)
	v_cvt_pk_bf16_f32 v2, v10, v8
	v_cndmask_b32_e32 v8, v35, v52, vcc
	s_addc_u32 s1, s16, 0
	v_lshlrev_b32_e32 v98, 1, v36
	v_or_b32_e32 v8, s15, v8
	v_lshl_add_u64 v[6:7], s[0:1], 0, v[98:99]
	v_mul_u32_u24_e32 v98, 0x300, v8
	v_cndmask_b32_e32 v8, v47, v53, vcc
	v_or_b32_e32 v8, s15, v8
	s_waitcnt lgkmcnt(4)
	v_cvt_pk_bf16_f32 v3, v12, v14
	s_waitcnt lgkmcnt(2)
	v_cvt_pk_bf16_f32 v4, v16, v18
	s_waitcnt lgkmcnt(0)
	v_cvt_pk_bf16_f32 v5, v20, v22
	v_lshl_add_u64 v[24:25], v[6:7], 0, v[98:99]
	v_mul_u32_u24_e32 v98, 0x300, v8
	global_store_dwordx4 v[24:25], v[2:5], off sc1
	s_nop 1
	v_cvt_pk_bf16_f32 v2, v11, v9
	v_cvt_pk_bf16_f32 v3, v13, v15
	v_cvt_pk_bf16_f32 v4, v17, v19
	v_cvt_pk_bf16_f32 v5, v21, v23
	v_lshl_add_u64 v[8:9], v[6:7], 0, v[98:99]
	global_store_dwordx4 v[8:9], v[2:5], off sc1
	ds_read2_b32 v[8:9], v50 offset0:16 offset1:24
	ds_read2_b32 v[10:11], v50 offset0:49 offset1:57
	ds_read2_b32 v[12:13], v50 offset0:82 offset1:90
	ds_read2_b32 v[14:15], v50 offset0:115 offset1:123
	ds_read2_b32 v[16:17], v50 offset0:148 offset1:156
	ds_read2_b32 v[18:19], v50 offset0:181 offset1:189
	ds_read2_b32 v[20:21], v50 offset0:214 offset1:222
	ds_read2_b32 v[22:23], v50 offset0:247 offset1:255
	s_waitcnt lgkmcnt(6)
	v_cvt_pk_bf16_f32 v2, v8, v10
	v_cndmask_b32_e32 v8, v48, v54, vcc
	v_or_b32_e32 v8, s15, v8
	v_mul_u32_u24_e32 v98, 0x300, v8
	v_cndmask_b32_e32 v8, v49, v55, vcc
	v_or_b32_e32 v8, s15, v8
	s_waitcnt lgkmcnt(4)
	v_cvt_pk_bf16_f32 v3, v12, v14
	s_waitcnt lgkmcnt(2)
	v_cvt_pk_bf16_f32 v4, v16, v18
	s_waitcnt lgkmcnt(0)
	v_cvt_pk_bf16_f32 v5, v20, v22
	v_lshl_add_u64 v[24:25], v[6:7], 0, v[98:99]
	v_mul_u32_u24_e32 v98, 0x300, v8
	global_store_dwordx4 v[24:25], v[2:5], off sc1
	v_lshl_add_u64 v[6:7], v[6:7], 0, v[98:99]
	s_nop 0
	v_cvt_pk_bf16_f32 v2, v9, v11
	v_cvt_pk_bf16_f32 v3, v13, v15
	v_cvt_pk_bf16_f32 v4, v17, v19
	v_cvt_pk_bf16_f32 v5, v21, v23
	global_store_dwordx4 v[6:7], v[2:5], off sc1
	s_waitcnt lgkmcnt(0)

.LBB0_1445:
	s_andn2_b64 vcc, exec, s[0:1]
	s_cbranch_vccnz .LBB0_1447
	s_lshl_b32 s12, s11, 3
	s_add_i32 s68, s12, 0xffffe7c0
	s_lshl_b64 s[0:1], s[68:69], 11
	s_mov_b32 s68, s69
	s_add_u32 s0, s9, s0
	s_mov_b32 s70, s69
	s_mov_b32 s71, s69
	v_mov_b64_e32 v[2:3], s[68:69]
	s_addc_u32 s1, s10, s1
	v_mov_b64_e32 v[4:5], s[70:71]
	s_add_i32 s68, s12, 0xffffe7c1
	global_store_dwordx4 v56, v[2:5], s[0:1] sc1
	global_store_dwordx4 v56, v[2:5], s[0:1] offset:1024 sc1
	s_lshl_b64 s[0:1], s[68:69], 11
	s_add_u32 s0, s9, s0
	s_addc_u32 s1, s10, s1
	s_add_i32 s68, s12, 0xffffe7c2
	global_store_dwordx4 v56, v[2:5], s[0:1] sc1
	global_store_dwordx4 v56, v[2:5], s[0:1] offset:1024 sc1
	s_lshl_b64 s[0:1], s[68:69], 11
	s_add_u32 s0, s9, s0
	s_addc_u32 s1, s10, s1
	s_add_i32 s68, s12, 0xffffe7c3
	global_store_dwordx4 v56, v[2:5], s[0:1] sc1
	global_store_dwordx4 v56, v[2:5], s[0:1] offset:1024 sc1
	s_lshl_b64 s[0:1], s[68:69], 11
	s_add_u32 s0, s9, s0
	s_addc_u32 s1, s10, s1
	s_add_i32 s68, s12, 0xffffe7c4
	global_store_dwordx4 v56, v[2:5], s[0:1] sc1
	global_store_dwordx4 v56, v[2:5], s[0:1] offset:1024 sc1
	s_lshl_b64 s[0:1], s[68:69], 11
	s_add_u32 s0, s9, s0
	s_addc_u32 s1, s10, s1
	s_add_i32 s68, s12, 0xffffe7c5
	global_store_dwordx4 v56, v[2:5], s[0:1] sc1
	global_store_dwordx4 v56, v[2:5], s[0:1] offset:1024 sc1
	s_lshl_b64 s[0:1], s[68:69], 11
	s_add_u32 s0, s9, s0
	s_addc_u32 s1, s10, s1
	s_add_i32 s68, s12, 0xffffe7c6
	global_store_dwordx4 v56, v[2:5], s[0:1] sc1
	global_store_dwordx4 v56, v[2:5], s[0:1] offset:1024 sc1
	s_lshl_b64 s[0:1], s[68:69], 11
	s_add_u32 s0, s9, s0
	s_addc_u32 s1, s10, s1
	s_add_i32 s68, s12, 0xffffe7c7
	global_store_dwordx4 v56, v[2:5], s[0:1] sc1
	global_store_dwordx4 v56, v[2:5], s[0:1] offset:1024 sc1
	s_lshl_b64 s[0:1], s[68:69], 11
	s_add_u32 s0, s9, s0
	s_addc_u32 s1, s10, s1
	global_store_dwordx4 v56, v[2:5], s[0:1] sc1
	global_store_dwordx4 v56, v[2:5], s[0:1] offset:1024 sc1

.LBB0_1448:
	s_andn2_b64 vcc, exec, s[0:1]
	s_cbranch_vccnz .LBB0_1450
	s_lshl_b32 s0, s11, 3
	s_and_b32 s0, s0, 0x1fc0
	s_add_i32 s68, s0, 0xffffe900
	s_lshl_b32 s0, s2, 5
	s_and_b32 s1, s0, 0xe0
	s_or_b32 s0, s1, 0x800
	s_lshl_b32 s1, s1, 2
	s_add_u32 s12, s22, s1
	v_or_b32_e32 v4, s68, v35
	s_addc_u32 s13, s23, 0
	v_lshlrev_b32_e32 v98, 2, v34
	v_lshl_add_u64 v[2:3], s[12:13], 0, v[98:99]
	v_mul_i32_i24_e32 v98, 0x1b00, v4
	v_lshl_add_u64 v[30:31], v[2:3], 0, v[98:99]
	s_mov_b32 s1, 0xe000
	v_add_co_u32_e32 v6, vcc, s1, v30
	global_load_dwordx4 v[2:5], v[30:31], off offset:2816 nt
	s_nop 0
	v_addc_co_u32_e32 v7, vcc, 0, v31, vcc
	s_mov_b32 s1, 0x1b000
	global_load_dwordx4 v[6:9], v[6:7], off offset:768 nt
	v_add_co_u32_e32 v10, vcc, s1, v30
	s_mov_b32 s1, 0x29000
	s_nop 0
	v_addc_co_u32_e32 v11, vcc, 0, v31, vcc
	global_load_dwordx4 v[10:13], v[10:11], off offset:2816 nt
	v_add_co_u32_e32 v14, vcc, s1, v30
	s_mov_b32 s1, 0x36000
	s_nop 0
	v_addc_co_u32_e32 v15, vcc, 0, v31, vcc
	global_load_dwordx4 v[14:17], v[14:15], off offset:768 nt
	v_add_co_u32_e32 v18, vcc, s1, v30
	s_mov_b32 s1, 0x44000
	s_nop 0
	v_addc_co_u32_e32 v19, vcc, 0, v31, vcc
	global_load_dwordx4 v[18:21], v[18:19], off offset:2816 nt
	v_add_co_u32_e32 v22, vcc, s1, v30
	s_mov_b32 s1, 0x51000
	s_nop 0
	v_addc_co_u32_e32 v23, vcc, 0, v31, vcc
	global_load_dwordx4 v[22:25], v[22:23], off offset:768 nt
	v_add_co_u32_e32 v26, vcc, s1, v30
	s_mov_b32 s1, 0x5f000
	s_nop 0
	v_addc_co_u32_e32 v27, vcc, 0, v31, vcc
	global_load_dwordx4 v[26:29], v[26:27], off offset:2816 nt
	v_add_co_u32_e32 v30, vcc, s1, v30
	v_add_u32_e32 v41, v37, v45
	s_nop 0
	v_addc_co_u32_e32 v31, vcc, 0, v31, vcc
	global_load_dwordx4 v[30:33], v[30:31], off offset:768 nt
	s_lshl_b64 s[12:13], s[68:69], 1
	s_add_u32 s12, s9, s12
	s_addc_u32 s13, s10, s13
	v_lshlrev_b32_e32 v98, 1, v36
	s_waitcnt vmcnt(0)
	ds_write2_b32 v41, v2, v3 offset1:1
	ds_write2_b32 v41, v4, v5 offset0:2 offset1:3
	v_add_u32_e32 v2, 0x420, v41
	ds_write2_b32 v2, v6, v7 offset1:1
	v_add_u32_e32 v2, 0x428, v41
	ds_write2_b32 v2, v8, v9 offset1:1
	v_add_u32_e32 v2, 0x840, v41
	v_lshl_add_u64 v[6:7], s[12:13], 0, v[98:99]
	ds_write2_b32 v2, v10, v11 offset1:1
	v_add_u32_e32 v2, 0x848, v41
	ds_write2_b32 v2, v12, v13 offset1:1
	v_add_u32_e32 v2, 0xc60, v41
	ds_write2_b32 v2, v14, v15 offset1:1
	v_add_u32_e32 v2, 0xc68, v41
	ds_write2_b32 v2, v16, v17 offset1:1
	v_add_u32_e32 v2, 0x1080, v41
	ds_write2_b32 v2, v18, v19 offset1:1
	v_add_u32_e32 v2, 0x1088, v41
	ds_write2_b32 v2, v20, v21 offset1:1
	v_add_u32_e32 v2, 0x14a0, v41
	ds_write2_b32 v2, v22, v23 offset1:1
	v_add_u32_e32 v2, 0x14a8, v41
	ds_write2_b32 v2, v24, v25 offset1:1
	v_add_u32_e32 v2, 0x18c0, v41
	ds_write2_b32 v2, v26, v27 offset1:1
	v_add_u32_e32 v2, 0x18c8, v41
	ds_write2_b32 v2, v28, v29 offset1:1
	v_add_u32_e32 v2, 0x1ce0, v41
	ds_write2_b32 v2, v30, v31 offset1:1
	v_add_u32_e32 v2, 0x1ce8, v41
	ds_write2_b32 v2, v32, v33 offset1:1
	s_waitcnt lgkmcnt(0)
	ds_read2_b32 v[8:9], v50 offset0:33 offset1:41
	ds_read2_b32 v[10:11], v50 offset1:8
	ds_read2_b32 v[12:13], v50 offset0:66 offset1:74
	ds_read2_b32 v[14:15], v50 offset0:99 offset1:107
	ds_read2_b32 v[16:17], v50 offset0:132 offset1:140
	ds_read2_b32 v[18:19], v50 offset0:165 offset1:173
	ds_read2_b32 v[20:21], v50 offset0:198 offset1:206
	ds_read2_b32 v[22:23], v50 offset0:231 offset1:239
	s_waitcnt lgkmcnt(6)
	v_cvt_pk_bf16_f32 v2, v10, v8
	v_or_b32_e32 v8, s0, v35
	v_lshlrev_b32_e32 v98, 11, v8
	v_or_b32_e32 v8, s0, v47
	s_waitcnt lgkmcnt(4)
	v_cvt_pk_bf16_f32 v3, v12, v14
	s_waitcnt lgkmcnt(2)
	v_cvt_pk_bf16_f32 v4, v16, v18
	s_waitcnt lgkmcnt(0)
	v_cvt_pk_bf16_f32 v5, v20, v22
	v_lshl_add_u64 v[24:25], v[6:7], 0, v[98:99]
	v_lshlrev_b32_e32 v98, 11, v8
	global_store_dwordx4 v[24:25], v[2:5], off sc1
	s_nop 1
	v_cvt_pk_bf16_f32 v2, v11, v9
	v_cvt_pk_bf16_f32 v3, v13, v15
	v_cvt_pk_bf16_f32 v4, v17, v19
	v_cvt_pk_bf16_f32 v5, v21, v23
	v_lshl_add_u64 v[8:9], v[6:7], 0, v[98:99]
	global_store_dwordx4 v[8:9], v[2:5], off sc1
	ds_read2_b32 v[8:9], v50 offset0:49 offset1:57
	ds_read2_b32 v[10:11], v50 offset0:16 offset1:24
	ds_read2_b32 v[12:13], v50 offset0:82 offset1:90
	ds_read2_b32 v[14:15], v50 offset0:115 offset1:123
	ds_read2_b32 v[16:17], v50 offset0:148 offset1:156
	ds_read2_b32 v[18:19], v50 offset0:181 offset1:189
	ds_read2_b32 v[20:21], v50 offset0:214 offset1:222
	ds_read2_b32 v[22:23], v50 offset0:247 offset1:255
	s_waitcnt lgkmcnt(6)
	v_cvt_pk_bf16_f32 v2, v10, v8
	v_or_b32_e32 v8, s0, v48
	v_lshlrev_b32_e32 v98, 11, v8
	v_or_b32_e32 v8, s0, v49
	s_waitcnt lgkmcnt(4)
	v_cvt_pk_bf16_f32 v3, v12, v14
	s_waitcnt lgkmcnt(2)
	v_cvt_pk_bf16_f32 v4, v16, v18
	s_waitcnt lgkmcnt(0)
	v_cvt_pk_bf16_f32 v5, v20, v22
	v_lshl_add_u64 v[24:25], v[6:7], 0, v[98:99]
	v_lshlrev_b32_e32 v98, 11, v8
	global_store_dwordx4 v[24:25], v[2:5], off sc1
	v_lshl_add_u64 v[6:7], v[6:7], 0, v[98:99]
	s_nop 0
	v_cvt_pk_bf16_f32 v2, v11, v9
	v_cvt_pk_bf16_f32 v3, v13, v15
	v_cvt_pk_bf16_f32 v4, v17, v19
	v_cvt_pk_bf16_f32 v5, v21, v23
	global_store_dwordx4 v[6:7], v[2:5], off sc1
	s_waitcnt lgkmcnt(0)

.LBB0_1451:
	s_andn2_b64 vcc, exec, s[0:1]
	s_cbranch_vccnz .LBB0_1453
	s_add_i32 s0, s11, 0xfea0
	s_and_b32 s1, s0, 0xffff
	s_mul_i32 s1, s1, 0xaaab
	s_lshr_b32 s1, s1, 20
	s_mul_i32 s12, s1, 24
	s_sub_i32 s12, s0, s12
	s_lshl_b32 s0, s12, 5
	s_addk_i32 s0, 0x500
	s_lshl_b32 s12, s12, 7
	s_and_b32 s0, s0, 0xffe0
	s_and_b32 s12, s12, 0x3ff80
	s_add_u32 s12, s22, s12
	v_lshl_or_b32 v4, s1, 6, v35
	s_addc_u32 s13, s23, 0
	v_lshlrev_b32_e32 v98, 2, v34
	v_lshl_add_u64 v[2:3], s[12:13], 0, v[98:99]
	v_mul_u32_u24_e32 v98, 0x1b00, v4
	v_lshl_add_u64 v[30:31], v[2:3], 0, v[98:99]
	s_mov_b32 s12, 0xe000
	v_add_co_u32_e32 v6, vcc, s12, v30
	global_load_dwordx4 v[2:5], v[30:31], off offset:3840 nt
	s_nop 0
	v_addc_co_u32_e32 v7, vcc, 0, v31, vcc
	s_mov_b32 s12, 0x1b000
	global_load_dwordx4 v[6:9], v[6:7], off offset:1792 nt
	v_add_co_u32_e32 v10, vcc, s12, v30
	s_mov_b32 s12, 0x29000
	s_nop 0
	v_addc_co_u32_e32 v11, vcc, 0, v31, vcc
	global_load_dwordx4 v[10:13], v[10:11], off offset:3840 nt
	v_add_co_u32_e32 v14, vcc, s12, v30
	s_mov_b32 s12, 0x36000
	s_nop 0
	v_addc_co_u32_e32 v15, vcc, 0, v31, vcc
	global_load_dwordx4 v[14:17], v[14:15], off offset:1792 nt
	v_add_co_u32_e32 v18, vcc, s12, v30
	s_mov_b32 s12, 0x44000
	s_nop 0
	v_addc_co_u32_e32 v19, vcc, 0, v31, vcc
	global_load_dwordx4 v[18:21], v[18:19], off offset:3840 nt
	v_add_co_u32_e32 v22, vcc, s12, v30
	s_mov_b32 s12, 0x51000
	s_nop 0
	v_addc_co_u32_e32 v23, vcc, 0, v31, vcc
	global_load_dwordx4 v[22:25], v[22:23], off offset:1792 nt
	v_add_co_u32_e32 v26, vcc, s12, v30
	s_mov_b32 s12, 0x5f000
	s_nop 0
	v_addc_co_u32_e32 v27, vcc, 0, v31, vcc
	global_load_dwordx4 v[26:29], v[26:27], off offset:3840 nt
	v_add_co_u32_e32 v30, vcc, s12, v30
	v_add_u32_e32 v41, v37, v45
	s_nop 0
	v_addc_co_u32_e32 v31, vcc, 0, v31, vcc
	global_load_dwordx4 v[30:33], v[30:31], off offset:1792 nt
	s_lshl_b32 s1, s1, 7
	s_add_u32 s12, s9, s1
	s_addc_u32 s13, s10, 0
	v_lshlrev_b32_e32 v98, 1, v36
	s_waitcnt vmcnt(0)
	ds_write2_b32 v41, v2, v3 offset1:1
	ds_write2_b32 v41, v4, v5 offset0:2 offset1:3
	v_add_u32_e32 v2, 0x420, v41
	ds_write2_b32 v2, v6, v7 offset1:1
	v_add_u32_e32 v2, 0x428, v41
	ds_write2_b32 v2, v8, v9 offset1:1
	v_add_u32_e32 v2, 0x840, v41
	v_lshl_add_u64 v[6:7], s[12:13], 0, v[98:99]
	ds_write2_b32 v2, v10, v11 offset1:1
	v_add_u32_e32 v2, 0x848, v41
	ds_write2_b32 v2, v12, v13 offset1:1
	v_add_u32_e32 v2, 0xc60, v41
	ds_write2_b32 v2, v14, v15 offset1:1
	v_add_u32_e32 v2, 0xc68, v41
	ds_write2_b32 v2, v16, v17 offset1:1
	v_add_u32_e32 v2, 0x1080, v41
	ds_write2_b32 v2, v18, v19 offset1:1
	v_add_u32_e32 v2, 0x1088, v41
	ds_write2_b32 v2, v20, v21 offset1:1
	v_add_u32_e32 v2, 0x14a0, v41
	ds_write2_b32 v2, v22, v23 offset1:1
	v_add_u32_e32 v2, 0x14a8, v41
	ds_write2_b32 v2, v24, v25 offset1:1
	v_add_u32_e32 v2, 0x18c0, v41
	ds_write2_b32 v2, v26, v27 offset1:1
	v_add_u32_e32 v2, 0x18c8, v41
	ds_write2_b32 v2, v28, v29 offset1:1
	v_add_u32_e32 v2, 0x1ce0, v41
	ds_write2_b32 v2, v30, v31 offset1:1
	v_add_u32_e32 v2, 0x1ce8, v41
	ds_write2_b32 v2, v32, v33 offset1:1
	s_waitcnt lgkmcnt(0)
	ds_read2_b32 v[8:9], v50 offset0:33 offset1:41
	ds_read2_b32 v[10:11], v50 offset1:8
	ds_read2_b32 v[12:13], v50 offset0:66 offset1:74
	ds_read2_b32 v[14:15], v50 offset0:99 offset1:107
	ds_read2_b32 v[16:17], v50 offset0:132 offset1:140
	ds_read2_b32 v[18:19], v50 offset0:165 offset1:173
	ds_read2_b32 v[20:21], v50 offset0:198 offset1:206
	ds_read2_b32 v[22:23], v50 offset0:231 offset1:239
	s_waitcnt lgkmcnt(6)
	v_cvt_pk_bf16_f32 v2, v10, v8
	v_or_b32_e32 v8, s0, v35
	v_lshlrev_b32_e32 v98, 11, v8
	v_or_b32_e32 v8, s0, v47
	s_waitcnt lgkmcnt(4)
	v_cvt_pk_bf16_f32 v3, v12, v14
	s_waitcnt lgkmcnt(2)
	v_cvt_pk_bf16_f32 v4, v16, v18
	s_waitcnt lgkmcnt(0)
	v_cvt_pk_bf16_f32 v5, v20, v22
	v_lshl_add_u64 v[24:25], v[6:7], 0, v[98:99]
	v_lshlrev_b32_e32 v98, 11, v8
	global_store_dwordx4 v[24:25], v[2:5], off sc1
	s_nop 1
	v_cvt_pk_bf16_f32 v2, v11, v9
	v_cvt_pk_bf16_f32 v3, v13, v15
	v_cvt_pk_bf16_f32 v4, v17, v19
	v_cvt_pk_bf16_f32 v5, v21, v23
	v_lshl_add_u64 v[8:9], v[6:7], 0, v[98:99]
	global_store_dwordx4 v[8:9], v[2:5], off sc1
	ds_read2_b32 v[8:9], v50 offset0:49 offset1:57
	ds_read2_b32 v[10:11], v50 offset0:16 offset1:24
	ds_read2_b32 v[12:13], v50 offset0:82 offset1:90
	ds_read2_b32 v[14:15], v50 offset0:115 offset1:123
	ds_read2_b32 v[16:17], v50 offset0:148 offset1:156
	ds_read2_b32 v[18:19], v50 offset0:181 offset1:189
	ds_read2_b32 v[20:21], v50 offset0:214 offset1:222
	ds_read2_b32 v[22:23], v50 offset0:247 offset1:255
	s_waitcnt lgkmcnt(6)
	v_cvt_pk_bf16_f32 v2, v10, v8
	v_or_b32_e32 v8, s0, v48
	v_lshlrev_b32_e32 v98, 11, v8
	v_or_b32_e32 v8, s0, v49
	s_waitcnt lgkmcnt(4)
	v_cvt_pk_bf16_f32 v3, v12, v14
	s_waitcnt lgkmcnt(2)
	v_cvt_pk_bf16_f32 v4, v16, v18
	s_waitcnt lgkmcnt(0)
	v_cvt_pk_bf16_f32 v5, v20, v22
	v_lshl_add_u64 v[24:25], v[6:7], 0, v[98:99]
	v_lshlrev_b32_e32 v98, 11, v8
	global_store_dwordx4 v[24:25], v[2:5], off sc1
	v_lshl_add_u64 v[6:7], v[6:7], 0, v[98:99]
	s_nop 0
	v_cvt_pk_bf16_f32 v2, v11, v9
	v_cvt_pk_bf16_f32 v3, v13, v15
	v_cvt_pk_bf16_f32 v4, v17, v19
	v_cvt_pk_bf16_f32 v5, v21, v23
	global_store_dwordx4 v[6:7], v[2:5], off sc1
	s_waitcnt lgkmcnt(0)

.LBB0_1454:
	s_andn2_b64 vcc, exec, s[0:1]
	s_cbranch_vccnz .LBB0_1382
	s_mul_hi_i32 s0, s11, 0x2e8ba2e9
	s_lshr_b32 s1, s0, 31
	s_ashr_i32 s0, s0, 2
	s_add_i32 s0, s0, s1
	s_mul_i32 s1, s0, 22
	s_sub_i32 s1, s11, s1
	s_lshl_b32 s36, s0, 6
	s_lshl_b32 s0, s1, 5
	s_ashr_i32 s1, s0, 31
	s_lshl_b64 s[12:13], s[0:1], 2
	s_add_u32 s12, s22, s12
	s_addc_u32 s13, s23, s13
	v_lshlrev_b32_e32 v98, 2, v34
	v_or_b32_e32 v32, s36, v35
	v_lshl_add_u64 v[30:31], s[12:13], 0, v[98:99]
	s_movk_i32 s1, 0x1b00
	v_mad_i64_i32 v[2:3], s[12:13], v32, s1, v[30:31]
	v_or_b32_e32 v6, 8, v32
	global_load_dwordx4 v[2:5], v[2:3], off nt
	v_mad_i64_i32 v[6:7], s[12:13], v6, s1, v[30:31]
	global_load_dwordx4 v[6:9], v[6:7], off nt
	v_or_b32_e32 v10, 16, v32
	v_mad_i64_i32 v[10:11], s[12:13], v10, s1, v[30:31]
	global_load_dwordx4 v[10:13], v[10:11], off nt
	v_or_b32_e32 v14, 24, v32
	v_mad_i64_i32 v[14:15], s[12:13], v14, s1, v[30:31]
	global_load_dwordx4 v[14:17], v[14:15], off nt
	v_or_b32_e32 v18, 32, v32
	v_mad_i64_i32 v[18:19], s[12:13], v18, s1, v[30:31]
	global_load_dwordx4 v[18:21], v[18:19], off nt
	v_or_b32_e32 v22, 40, v32
	v_mad_i64_i32 v[22:23], s[12:13], v22, s1, v[30:31]
	global_load_dwordx4 v[22:25], v[22:23], off nt
	v_or_b32_e32 v26, 48, v32
	v_mad_i64_i32 v[26:27], s[12:13], v26, s1, v[30:31]
	global_load_dwordx4 v[26:29], v[26:27], off nt
	v_or_b32_e32 v32, 56, v32
	v_mad_i64_i32 v[30:31], s[12:13], v32, s1, v[30:31]
	global_load_dwordx4 v[30:33], v[30:31], off nt
	v_add_u32_e32 v41, v37, v45
	s_ashr_i32 s37, s36, 31
	s_lshl_b64 s[12:13], s[36:37], 1
	s_add_u32 s12, s9, s12
	s_addc_u32 s13, s10, s13
	v_lshlrev_b32_e32 v98, 1, v36
	s_waitcnt vmcnt(0)
	ds_write2_b32 v41, v2, v3 offset1:1
	ds_write2_b32 v41, v4, v5 offset0:2 offset1:3
	v_add_u32_e32 v2, 0x420, v41
	ds_write2_b32 v2, v6, v7 offset1:1
	v_add_u32_e32 v2, 0x428, v41
	ds_write2_b32 v2, v8, v9 offset1:1
	v_add_u32_e32 v2, 0x840, v41
	ds_write2_b32 v2, v10, v11 offset1:1
	v_add_u32_e32 v2, 0x848, v41
	ds_write2_b32 v2, v12, v13 offset1:1
	v_add_u32_e32 v2, 0xc60, v41
	ds_write2_b32 v2, v14, v15 offset1:1
	v_add_u32_e32 v2, 0xc68, v41
	ds_write2_b32 v2, v16, v17 offset1:1
	v_add_u32_e32 v2, 0x1080, v41
	ds_write2_b32 v2, v18, v19 offset1:1
	v_add_u32_e32 v2, 0x1088, v41
	ds_write2_b32 v2, v20, v21 offset1:1
	v_add_u32_e32 v2, 0x14a0, v41
	ds_write2_b32 v2, v22, v23 offset1:1
	v_add_u32_e32 v2, 0x14a8, v41
	ds_write2_b32 v2, v24, v25 offset1:1
	v_add_u32_e32 v2, 0x18c0, v41
	ds_write2_b32 v2, v26, v27 offset1:1
	v_add_u32_e32 v2, 0x18c8, v41
	ds_write2_b32 v2, v28, v29 offset1:1
	v_add_u32_e32 v2, 0x1ce0, v41
	ds_write2_b32 v2, v30, v31 offset1:1
	v_add_u32_e32 v2, 0x1ce8, v41
	ds_write2_b32 v2, v32, v33 offset1:1
	s_waitcnt lgkmcnt(0)
	ds_read2_b32 v[8:9], v50 offset0:33 offset1:41
	ds_read2_b32 v[10:11], v50 offset1:8
	ds_read2_b32 v[12:13], v50 offset0:66 offset1:74
	ds_read2_b32 v[14:15], v50 offset0:99 offset1:107
	ds_read2_b32 v[16:17], v50 offset0:132 offset1:140
	ds_read2_b32 v[18:19], v50 offset0:165 offset1:173
	ds_read2_b32 v[20:21], v50 offset0:198 offset1:206
	ds_read2_b32 v[22:23], v50 offset0:231 offset1:239
	v_or_b32_e32 v24, s0, v35
	v_ashrrev_i32_e32 v25, 31, v24
	v_lshl_add_u64 v[6:7], s[12:13], 0, v[98:99]
	v_lshlrev_b64 v[24:25], 11, v[24:25]
	s_waitcnt lgkmcnt(6)
	v_cvt_pk_bf16_f32 v2, v10, v8
	s_waitcnt lgkmcnt(4)
	v_cvt_pk_bf16_f32 v3, v12, v14
	s_waitcnt lgkmcnt(2)
	v_cvt_pk_bf16_f32 v4, v16, v18
	s_waitcnt lgkmcnt(0)
	v_cvt_pk_bf16_f32 v5, v20, v22
	v_lshl_add_u64 v[24:25], v[6:7], 0, v[24:25]
	v_or_b32_e32 v8, s0, v47
	global_store_dwordx4 v[24:25], v[2:5], off sc1
	v_or_b32_e32 v24, s0, v48
	v_ashrrev_i32_e32 v25, 31, v24
	v_cvt_pk_bf16_f32 v2, v11, v9
	v_ashrrev_i32_e32 v9, 31, v8
	v_lshlrev_b64 v[8:9], 11, v[8:9]
	v_cvt_pk_bf16_f32 v3, v13, v15
	v_cvt_pk_bf16_f32 v4, v17, v19
	v_cvt_pk_bf16_f32 v5, v21, v23
	v_lshl_add_u64 v[8:9], v[6:7], 0, v[8:9]
	global_store_dwordx4 v[8:9], v[2:5], off sc1
	ds_read2_b32 v[8:9], v50 offset0:49 offset1:57
	ds_read2_b32 v[10:11], v50 offset0:16 offset1:24
	ds_read2_b32 v[12:13], v50 offset0:82 offset1:90
	ds_read2_b32 v[14:15], v50 offset0:115 offset1:123
	ds_read2_b32 v[16:17], v50 offset0:148 offset1:156
	ds_read2_b32 v[18:19], v50 offset0:181 offset1:189
	ds_read2_b32 v[20:21], v50 offset0:214 offset1:222
	ds_read2_b32 v[22:23], v50 offset0:247 offset1:255
	v_lshlrev_b64 v[24:25], 11, v[24:25]
	s_waitcnt lgkmcnt(6)
	v_cvt_pk_bf16_f32 v2, v10, v8
	s_waitcnt lgkmcnt(4)
	v_cvt_pk_bf16_f32 v3, v12, v14
	s_waitcnt lgkmcnt(2)
	v_cvt_pk_bf16_f32 v4, v16, v18
	s_waitcnt lgkmcnt(0)
	v_cvt_pk_bf16_f32 v5, v20, v22
	v_lshl_add_u64 v[24:25], v[6:7], 0, v[24:25]
	v_or_b32_e32 v8, s0, v49
	global_store_dwordx4 v[24:25], v[2:5], off sc1
	s_nop 1
	v_cvt_pk_bf16_f32 v2, v11, v9
	v_ashrrev_i32_e32 v9, 31, v8
	v_lshlrev_b64 v[8:9], 11, v[8:9]
	v_cvt_pk_bf16_f32 v3, v13, v15
	v_cvt_pk_bf16_f32 v4, v17, v19
	v_cvt_pk_bf16_f32 v5, v21, v23
	v_lshl_add_u64 v[6:7], v[6:7], 0, v[8:9]
	global_store_dwordx4 v[6:7], v[2:5], off sc1
	s_waitcnt lgkmcnt(0)
	s_branch .LBB0_1382
